# UP epilogue: first wait covers only the 8 row-statistics loads; conv-weight loads waited after the halo exports (counted)
# baseline (speedup 1.0000x reference)
.LBB0_216:
	s_lshl_b32 s23, s34, 8
	s_add_i32 s23, s23, s54
	v_or_b32_e32 v237, s23, v231
	v_lshl_or_b32 v0, v237, 6, v193
	v_or_b32_e32 v240, 1, v237
	v_lshl_add_u64 v[70:71], s[10:11], 0, v[0:1]
	v_lshl_or_b32 v72, v240, 6, v193
	v_mov_b32_e32 v73, v1
	v_lshl_add_u64 v[72:73], s[10:11], 0, v[72:73]
	global_load_dwordx4 v[166:169], v[70:71], off
	global_load_dwordx4 v[170:173], v[72:73], off
	v_or_b32_e32 v239, 2, v237
	v_lshl_or_b32 v70, v239, 6, v193
	v_mov_b32_e32 v71, v1
	v_lshl_add_u64 v[70:71], s[10:11], 0, v[70:71]
	global_load_dwordx4 v[174:177], v[70:71], off
	v_or_b32_e32 v70, 0xc0, v0
	v_mov_b32_e32 v71, v1
	v_lshl_add_u64 v[70:71], s[10:11], 0, v[70:71]
	global_load_dwordx4 v[178:181], v[70:71], off
	v_add_u32_e32 v238, 0x80, v237
	v_mov_b32_e32 v71, v1
	v_lshl_or_b32 v70, v238, 6, v193
	v_lshl_add_u64 v[70:71], s[10:11], 0, v[70:71]
	global_load_dwordx4 v[242:245], v[70:71], off
	v_mov_b32_e32 v73, v1
	v_mov_b32_e32 v75, v1
	v_lshl_or_b32 v192, s30, 7, v235
	v_add_u32_e32 v72, 0x2040, v0
	v_add_u32_e32 v74, 0x2080, v0
	v_add_u32_e32 v0, 0x20c0, v0
	v_lshl_add_u64 v[72:73], s[10:11], 0, v[72:73]
	v_lshl_add_u64 v[70:71], s[10:11], 0, v[74:75]
	v_lshl_add_u64 v[74:75], s[10:11], 0, v[0:1]
	v_lshlrev_b32_e32 v0, 2, v192
	global_load_dwordx4 v[246:249], v[72:73], off
	global_load_dwordx4 v[250:253], v[70:71], off
	global_load_dwordx4 v[194:197], v[74:75], off
	v_lshl_add_u64 v[206:207], s[12:13], 0, v[0:1]
	s_movk_i32 s25, 0x6000
	v_add_co_u32_e32 v202, vcc, s25, v206
	s_mov_b32 s25, 0xc000
	s_nop 0
	v_addc_co_u32_e32 v203, vcc, 0, v207, vcc
	v_add_co_u32_e32 v208, vcc, s25, v206
	s_movk_i32 s25, 0x3000
	s_nop 0
	v_addc_co_u32_e32 v209, vcc, 0, v207, vcc
	v_add_co_u32_e32 v204, vcc, s25, v206
	s_mov_b32 s30, 0x9000
	s_nop 0
	v_addc_co_u32_e32 v205, vcc, 0, v207, vcc
	v_add_co_u32_e32 v210, vcc, s30, v206
	s_mov_b32 s30, 0xf000
	s_nop 0
	v_addc_co_u32_e32 v211, vcc, 0, v207, vcc
	v_add_co_u32_e32 v212, vcc, s30, v206
	v_lshl_add_u64 v[200:201], s[14:15], 0, v[0:1]
	s_nop 0
	v_addc_co_u32_e32 v213, vcc, 0, v207, vcc
	v_add_co_u32_e32 v214, vcc, s25, v200
	global_load_dwordx4 v[74:77], v[206:207], off
	global_load_dwordx4 v[78:81], v[200:201], off
	v_addc_co_u32_e32 v215, vcc, 0, v201, vcc
	global_load_dwordx4 v[98:101], v[202:203], off
	global_load_dwordx4 v[94:97], v[208:209], off
	global_load_dwordx4 v[86:89], v[204:205], off
	global_load_dwordx4 v[82:85], v[210:211], off
	global_load_dwordx4 v[70:73], v[212:213], off
	global_load_dwordx4 v[90:93], v[214:215], off
	s_waitcnt vmcnt(8) lgkmcnt(0)
	v_mov_b32_e32 v216, v167
	v_mov_b32_e32 v217, v168
	v_mov_b32_e32 v167, v169
	v_pk_add_f32 v[166:167], v[216:217], v[166:167]
	v_mov_b32_e32 v168, v171
	v_mov_b32_e32 v169, v172
	v_mov_b32_e32 v171, v173
	v_add_f32_e32 v0, v166, v167
	v_pk_add_f32 v[166:167], v[168:169], v[170:171]
	ds_bpermute_b32 v170, v233, v0
	v_mov_b32_e32 v172, v175
	v_mov_b32_e32 v173, v176
	v_mov_b32_e32 v175, v177
	v_mov_b32_e32 v176, v179
	v_mov_b32_e32 v177, v180
	v_pk_add_f32 v[168:169], v[172:173], v[174:175]
	v_mov_b32_e32 v179, v181
	v_add_f32_e32 v173, v168, v169
	v_pk_add_f32 v[168:169], v[176:177], v[178:179]
	v_add_f32_e32 v171, v166, v167
	s_waitcnt lgkmcnt(0)
	v_add_f32_e32 v166, v0, v170
	v_add_f32_e32 v0, v168, v169
	ds_bpermute_b32 v174, v233, v173
	ds_bpermute_b32 v175, v233, v0
	v_mov_b32_e32 v168, v243
	v_mov_b32_e32 v169, v244
	v_mov_b32_e32 v243, v245
	v_pk_add_f32 v[168:169], v[168:169], v[242:243]
	s_waitcnt lgkmcnt(0)
	v_add_f32_e32 v0, v0, v175
	v_add_f32_e32 v176, v168, v169
	ds_bpermute_b32 v177, v233, v176
	v_add_f32_e32 v169, v173, v174
	v_mov_b32_e32 v174, v247
	v_mov_b32_e32 v175, v248
	v_mov_b32_e32 v247, v249
	v_pk_add_f32 v[174:175], v[174:175], v[246:247]
	s_waitcnt lgkmcnt(0)
	v_add_f32_e32 v243, v176, v177
	v_add_f32_e32 v173, v174, v175
	v_mov_b32_e32 v174, v251
	v_mov_b32_e32 v175, v252
	v_mov_b32_e32 v251, v253
	v_pk_add_f32 v[174:175], v[174:175], v[250:251]
	ds_bpermute_b32 v172, v233, v171
	v_add_f32_e32 v177, v174, v175
	v_mov_b32_e32 v174, v195
	v_mov_b32_e32 v175, v196
	v_mov_b32_e32 v195, v197
	v_pk_add_f32 v[174:175], v[174:175], v[194:195]
	ds_bpermute_b32 v176, v233, v173
	v_add_f32_e32 v174, v174, v175
	ds_bpermute_b32 v178, v233, v177
	ds_bpermute_b32 v175, v233, v174
	s_waitcnt lgkmcnt(3)
	v_add_f32_e32 v170, v171, v172
	s_waitcnt lgkmcnt(2)
	v_add_f32_e32 v241, v173, v176
	ds_bpermute_b32 v167, v234, v166
	s_waitcnt lgkmcnt(2)
	v_add_f32_e32 v247, v177, v178
	s_waitcnt lgkmcnt(1)
	v_add_f32_e32 v245, v174, v175
	ds_bpermute_b32 v171, v234, v170
	ds_bpermute_b32 v244, v234, v243
	ds_bpermute_b32 v242, v234, v241
	ds_bpermute_b32 v248, v234, v247
	ds_bpermute_b32 v246, v234, v245
	ds_bpermute_b32 v172, v234, v169
	ds_bpermute_b32 v168, v234, v0
	s_waitcnt lgkmcnt(1)
	v_add_f32_e32 v169, v169, v172
	s_waitcnt lgkmcnt(0)
	v_add_f32_e32 v0, v0, v168
	v_fmamk_f32 v169, v169, 0x3a800000, v219
	v_fmamk_f32 v0, v0, 0x3a800000, v219
	v_rsq_f32_e32 v172, v169
	v_rsq_f32_e32 v0, v0
	s_lshr_b32 s25, s23, 4
	v_cmp_lt_i32_e32 vcc, 11, v5
	v_pk_mul_f32 v[152:153], v[152:153], v[172:173] op_sel_hi:[1,0]
	v_pk_mul_f32 v[150:151], v[150:151], v[172:173] op_sel_hi:[1,0]
	v_pk_mul_f32 v[24:25], v[24:25], v[172:173] op_sel_hi:[1,0]
	v_pk_mul_f32 v[22:23], v[22:23], v[172:173] op_sel_hi:[1,0]
	v_pk_mul_f32 v[148:149], v[148:149], v[172:173] op_sel_hi:[1,0]
	v_pk_mul_f32 v[146:147], v[146:147], v[172:173] op_sel_hi:[1,0]
	v_pk_mul_f32 v[20:21], v[20:21], v[172:173] op_sel_hi:[1,0]
	v_pk_mul_f32 v[18:19], v[18:19], v[172:173] op_sel_hi:[1,0]
	v_pk_mul_f32 v[164:165], v[164:165], v[0:1] op_sel_hi:[1,0]
	v_pk_mul_f32 v[162:163], v[162:163], v[0:1] op_sel_hi:[1,0]
	v_pk_mul_f32 v[36:37], v[36:37], v[0:1] op_sel_hi:[1,0]
	v_pk_mul_f32 v[34:35], v[34:35], v[0:1] op_sel_hi:[1,0]
	v_pk_mul_f32 v[160:161], v[160:161], v[0:1] op_sel_hi:[1,0]
	v_pk_mul_f32 v[158:159], v[158:159], v[0:1] op_sel_hi:[1,0]
	v_pk_mul_f32 v[32:33], v[32:33], v[0:1] op_sel_hi:[1,0]
	v_pk_mul_f32 v[30:31], v[30:31], v[0:1] op_sel_hi:[1,0]
	v_sub_u32_e32 v255, 15, v5
	v_min_u32_e32 v255, v255, v5
	v_and_b32_e32 v0, 1, v255
	v_lshrrev_b32_e32 v255, 1, v255
	v_mul_u32_u24_e32 v255, 0x3000, v255
	v_lshl_add_u32 v255, v0, 4, v255
	s_mov_b64 s[30:31], 0
	s_and_saveexec_b64 s[34:35], vcc
	s_xor_b64 s[34:35], exec, s[34:35]
	v_readlane_b32 s43, v254, 41
	v_readlane_b32 s42, v254, 42
	s_cbranch_execz .LBB0_222
	s_and_b32 s37, s23, 0xfc0
	s_cmpk_eq_i32 s37, 0xfc0
	s_cselect_b64 s[30:31], -1, 0
	s_lshr_b32 s36, s23, 11
	s_cmpk_lg_i32 s37, 0xfc0
	s_mul_i32 s37, s25, 0x1800
	v_add_u32_e32 v168, s37, v192
	v_lshl_add_u32 v0, v168, 2, v225
	v_add_u32_e32 v0, v0, v255
	v_lshl_add_u64 v[172:173], s[16:17], 0, v[0:1]
	v_mov_b32_e32 v178, v150
	v_mov_b32_e32 v179, v151
	v_mov_b32_e32 v180, v152
	v_mov_b32_e32 v181, v153
	v_mov_b32_dpp v178, v22 row_shl:1 row_mask:0xf bank_mask:0x8
	v_mov_b32_dpp v179, v23 row_shl:1 row_mask:0xf bank_mask:0x8
	v_mov_b32_dpp v180, v24 row_shl:1 row_mask:0xf bank_mask:0x8
	v_mov_b32_dpp v181, v25 row_shl:1 row_mask:0xf bank_mask:0x8
	v_mov_b32_dpp v178, v146 row_shl:2 row_mask:0xf bank_mask:0x8
	v_mov_b32_dpp v179, v147 row_shl:2 row_mask:0xf bank_mask:0x8
	v_mov_b32_dpp v180, v148 row_shl:2 row_mask:0xf bank_mask:0x8
	v_mov_b32_dpp v181, v149 row_shl:2 row_mask:0xf bank_mask:0x8
	v_mov_b32_dpp v178, v18 row_shl:3 row_mask:0xf bank_mask:0x8
	v_mov_b32_dpp v179, v19 row_shl:3 row_mask:0xf bank_mask:0x8
	v_mov_b32_dpp v180, v20 row_shl:3 row_mask:0xf bank_mask:0x8
	v_mov_b32_dpp v181, v21 row_shl:3 row_mask:0xf bank_mask:0x8
	global_store_dwordx4 v[172:173], v[178:181], off
	s_cbranch_scc1 .LBB0_219
	s_and_b32 s37, s36, 0x1ffffe
	s_mulk_i32 s37, 0x1800
	v_add_lshl_u32 v0, s37, v192, 2
	v_add_u32_e32 v0, v0, v255
	v_lshl_add_u64 v[172:173], s[18:19], 0, v[0:1]
	global_store_dwordx4 v[172:173], v[178:181], off

.Lmy_u1_nodefer:
	s_waitcnt vmcnt(8)
	v_mov_b32_e32 v170, v1
	v_mov_b32_e32 v171, v1
	v_mov_b32_e32 v106, v1
	v_mov_b32_dpp v170, v150 row_shr:1 row_mask:0xf bank_mask:0xf
	v_mov_b32_e32 v107, v1
	v_mov_b32_dpp v171, v151 row_shr:1 row_mask:0xf bank_mask:0xf
	v_mov_b32_dpp v106, v162 row_shr:1 row_mask:0xf bank_mask:0xf
	v_mov_b32_dpp v107, v163 row_shr:1 row_mask:0xf bank_mask:0xf
	v_pk_fma_f32 v[170:171], v[74:75], v[170:171], v[78:79]
	v_mov_b32_e32 v172, v1
	v_pk_fma_f32 v[170:171], v[98:99], v[106:107], v[170:171]
	v_mov_b32_e32 v173, v1
	v_pk_fma_f32 v[174:175], v[94:95], v[166:167], v[170:171]
	v_mov_b32_e32 v178, v1
	v_mul_f32_e32 v0, v174, v174
	v_fmamk_f32 v0, v0, 0xbdd2d3e2, v220
	v_mul_f32_e32 v0, v174, v0
	v_exp_f32_e32 v0, v0
	v_mov_b32_e32 v179, v1
	v_mov_b32_e32 v108, v1
	v_mov_b32_dpp v172, v152 row_shr:1 row_mask:0xf bank_mask:0xf
	v_add_f32_e32 v0, 1.0, v0
	v_rcp_f32_e32 v0, v0
	v_mov_b32_e32 v109, v1
	v_mov_b32_dpp v173, v153 row_shr:1 row_mask:0xf bank_mask:0xf
	v_mov_b32_e32 v170, v1
	v_mul_f32_e32 v0, v174, v0
	v_mul_f32_e32 v174, v175, v175
	v_fmamk_f32 v174, v174, 0xbdd2d3e2, v220
	v_mul_f32_e32 v174, v175, v174
	v_exp_f32_e32 v174, v174
	v_mov_b32_dpp v178, v146 row_shr:1 row_mask:0xf bank_mask:0xf
	v_mov_b32_e32 v171, v1
	v_mov_b32_dpp v179, v147 row_shr:1 row_mask:0xf bank_mask:0xf
	v_add_f32_e32 v174, 1.0, v174
	v_rcp_f32_e32 v174, v174
	v_mov_b32_dpp v108, v164 row_shr:1 row_mask:0xf bank_mask:0xf
	v_mov_b32_dpp v109, v165 row_shr:1 row_mask:0xf bank_mask:0xf
	v_pk_fma_f32 v[172:173], v[76:77], v[172:173], v[80:81]
	v_mov_b32_dpp v170, v158 row_shr:1 row_mask:0xf bank_mask:0xf
	v_mov_b32_dpp v171, v159 row_shr:1 row_mask:0xf bank_mask:0xf
	v_pk_fma_f32 v[178:179], v[86:87], v[178:179], v[90:91]
	v_pk_fma_f32 v[172:173], v[100:101], v[108:109], v[172:173]
	v_pk_fma_f32 v[178:179], v[82:83], v[170:171], v[178:179]
	v_pk_fma_f32 v[176:177], v[96:97], v[168:169], v[172:173]
	v_pk_fma_f32 v[178:179], v[70:71], v[154:155], v[178:179]
	v_mul_f32_e32 v174, v175, v174
	v_mul_f32_e32 v0, v0, v178
	v_mul_f32_e32 v174, v174, v179
	v_mul_f32_e32 v175, v177, v177
	v_cvt_pk_bf16_f32 v174, v0, v174
	v_mul_f32_e32 v0, v176, v176
	v_fmamk_f32 v175, v175, 0xbdd2d3e2, v220
	v_fmamk_f32 v0, v0, 0xbdd2d3e2, v220
	v_mul_f32_e32 v175, v177, v175
	v_mul_f32_e32 v0, v176, v0
	v_exp_f32_e32 v175, v175
	v_exp_f32_e32 v0, v0
	v_mov_b32_e32 v180, v1
	v_mov_b32_e32 v181, v1
	v_add_f32_e32 v175, 1.0, v175
	v_add_f32_e32 v0, 1.0, v0
	v_rcp_f32_e32 v175, v175
	v_mov_b32_e32 v172, v1
	v_mov_b32_dpp v180, v148 row_shr:1 row_mask:0xf bank_mask:0xf
	v_mov_b32_e32 v173, v1
	v_mov_b32_dpp v181, v149 row_shr:1 row_mask:0xf bank_mask:0xf
	v_rcp_f32_e32 v0, v0
	v_mov_b32_dpp v172, v160 row_shr:1 row_mask:0xf bank_mask:0xf
	v_mov_b32_dpp v173, v161 row_shr:1 row_mask:0xf bank_mask:0xf
	v_pk_fma_f32 v[180:181], v[88:89], v[180:181], v[92:93]
	v_mul_f32_e32 v175, v177, v175
	v_pk_fma_f32 v[180:181], v[84:85], v[172:173], v[180:181]
	v_mul_f32_e32 v0, v176, v0
	v_pk_fma_f32 v[180:181], v[72:73], v[156:157], v[180:181]
	s_nop 0
	v_mul_f32_e32 v175, v175, v181
	v_mul_f32_e32 v0, v0, v180
	v_cvt_pk_bf16_f32 v175, v0, v175
	s_and_saveexec_b64 s[30:31], s[4:5]
	s_cbranch_execz .LBB0_242
	s_movk_i32 s23, 0xc00
	v_mul_lo_u32 v0, v237, s23
	v_add_lshl_u32 v0, v0, v192, 1
	v_lshl_add_u64 v[176:177], s[8:9], 0, v[0:1]
	global_store_dwordx2 v[176:177], v[174:175], off
